# gla chunk-state scan: loads of the next 13-chunk batch issued before the current batch's dependent chain (two register sets, counted vmcnt)
# baseline (speedup 1.0000x reference)
.LBB0_221:
	v_ashrrev_i32_e32 v0, 12, v30
	v_mul_i32_i24_e32 v0, 0x82, v0
	v_ashrrev_i32_e32 v1, 31, v0
	v_lshlrev_b32_e32 v6, 1, v29
	v_lshlrev_b64 v[2:3], 14, v[0:1]
	s_movk_i32 s9, 0x3ffc
	v_lshlrev_b32_e32 v7, 2, v29
	v_lshlrev_b64 v[4:5], 8, v[0:1]
	v_and_or_b32 v2, v6, s9, v2
	s_movk_i32 s9, 0xf8
	v_readlane_b32 s10, v245, 58
	v_and_or_b32 v4, v7, s9, v4
	v_readlane_b32 s11, v245, 59
	v_mov_b32_e32 v12, 0
	v_mov_b32_e32 v12, 0
	v_mov_b32_e32 v13, v12
	s_sub_u32 s68, s50, 0x30000
	s_subb_u32 s69, s51, 0
	s_sub_u32 s70, s10, 0x600
	s_subb_u32 s71, s11, 0
	v_add_u32_e32 v60, 0x0, v2
	global_load_dword v73, v60, s[68:69]
	v_add_u32_e32 v61, 0x4000, v2
	global_load_dword v74, v61, s[68:69]
	v_add_u32_e32 v62, 0x8000, v2
	global_load_dword v75, v62, s[68:69]
	v_add_u32_e32 v63, 0xc000, v2
	global_load_dword v76, v63, s[68:69]
	v_add_u32_e32 v64, 0x10000, v2
	global_load_dword v77, v64, s[68:69]
	v_add_u32_e32 v65, 0x14000, v2
	global_load_dword v78, v65, s[68:69]
	v_add_u32_e32 v66, 0x18000, v2
	global_load_dword v79, v66, s[68:69]
	v_add_u32_e32 v67, 0x1c000, v2
	global_load_dword v80, v67, s[68:69]
	v_add_u32_e32 v68, 0x20000, v2
	global_load_dword v81, v68, s[68:69]
	v_add_u32_e32 v69, 0x24000, v2
	global_load_dword v82, v69, s[68:69]
	v_add_u32_e32 v70, 0x28000, v2
	global_load_dword v83, v70, s[68:69]
	v_add_u32_e32 v71, 0x2c000, v2
	global_load_dword v84, v71, s[68:69]
	v_add_u32_e32 v72, 0x30000, v2
	global_load_dword v85, v72, s[68:69]
	v_mov_b32_e32 v164, v4
	global_load_dwordx2 v[86:87], v164, s[70:71] offset:0
	global_load_dwordx2 v[88:89], v164, s[70:71] offset:256
	global_load_dwordx2 v[90:91], v164, s[70:71] offset:512
	global_load_dwordx2 v[92:93], v164, s[70:71] offset:768
	global_load_dwordx2 v[94:95], v164, s[70:71] offset:1024
	global_load_dwordx2 v[96:97], v164, s[70:71] offset:1280
	global_load_dwordx2 v[98:99], v164, s[70:71] offset:1536
	global_load_dwordx2 v[100:101], v164, s[70:71] offset:1792
	global_load_dwordx2 v[102:103], v164, s[70:71] offset:2048
	global_load_dwordx2 v[104:105], v164, s[70:71] offset:2304
	global_load_dwordx2 v[106:107], v164, s[70:71] offset:2560
	global_load_dwordx2 v[108:109], v164, s[70:71] offset:2816
	global_load_dwordx2 v[110:111], v164, s[70:71] offset:3072
	v_add_u32_e32 v112, 0x34000, v2
	global_load_dword v125, v112, s[68:69]
	v_add_u32_e32 v113, 0x38000, v2
	global_load_dword v126, v113, s[68:69]
	v_add_u32_e32 v114, 0x3c000, v2
	global_load_dword v127, v114, s[68:69]
	v_add_u32_e32 v115, 0x40000, v2
	global_load_dword v128, v115, s[68:69]
	v_add_u32_e32 v116, 0x44000, v2
	global_load_dword v129, v116, s[68:69]
	v_add_u32_e32 v117, 0x48000, v2
	global_load_dword v130, v117, s[68:69]
	v_add_u32_e32 v118, 0x4c000, v2
	global_load_dword v131, v118, s[68:69]
	v_add_u32_e32 v119, 0x50000, v2
	global_load_dword v132, v119, s[68:69]
	v_add_u32_e32 v120, 0x54000, v2
	global_load_dword v133, v120, s[68:69]
	v_add_u32_e32 v121, 0x58000, v2
	global_load_dword v134, v121, s[68:69]
	v_add_u32_e32 v122, 0x5c000, v2
	global_load_dword v135, v122, s[68:69]
	v_add_u32_e32 v123, 0x60000, v2
	global_load_dword v136, v123, s[68:69]
	v_add_u32_e32 v124, 0x64000, v2
	global_load_dword v137, v124, s[68:69]
	v_add_u32_e32 v165, 0xd00, v4
	global_load_dwordx2 v[138:139], v165, s[70:71] offset:0
	global_load_dwordx2 v[140:141], v165, s[70:71] offset:256
	global_load_dwordx2 v[142:143], v165, s[70:71] offset:512
	global_load_dwordx2 v[144:145], v165, s[70:71] offset:768
	global_load_dwordx2 v[146:147], v165, s[70:71] offset:1024
	global_load_dwordx2 v[148:149], v165, s[70:71] offset:1280
	global_load_dwordx2 v[150:151], v165, s[70:71] offset:1536
	global_load_dwordx2 v[152:153], v165, s[70:71] offset:1792
	global_load_dwordx2 v[154:155], v165, s[70:71] offset:2048
	global_load_dwordx2 v[156:157], v165, s[70:71] offset:2304
	global_load_dwordx2 v[158:159], v165, s[70:71] offset:2560
	global_load_dwordx2 v[160:161], v165, s[70:71] offset:2816
	global_load_dwordx2 v[162:163], v165, s[70:71] offset:3072
	s_waitcnt vmcnt(26)
	s_nop 0
	v_cvt_pk_bf16_f32 v16, v12, v13
	global_store_dword v60, v16, s[68:69]
	v_lshlrev_b32_e32 v14, 16, v73
	v_and_b32_e32 v15, 0xffff0000, v73
	v_pk_fma_f32 v[12:13], v[12:13], v[86:87], v[14:15]
	s_nop 0
	v_cvt_pk_bf16_f32 v16, v12, v13
	global_store_dword v61, v16, s[68:69]
	v_lshlrev_b32_e32 v14, 16, v74
	v_and_b32_e32 v15, 0xffff0000, v74
	v_pk_fma_f32 v[12:13], v[12:13], v[88:89], v[14:15]
	s_nop 0
	v_cvt_pk_bf16_f32 v16, v12, v13
	global_store_dword v62, v16, s[68:69]
	v_lshlrev_b32_e32 v14, 16, v75
	v_and_b32_e32 v15, 0xffff0000, v75
	v_pk_fma_f32 v[12:13], v[12:13], v[90:91], v[14:15]
	s_nop 0
	v_cvt_pk_bf16_f32 v16, v12, v13
	global_store_dword v63, v16, s[68:69]
	v_lshlrev_b32_e32 v14, 16, v76
	v_and_b32_e32 v15, 0xffff0000, v76
	v_pk_fma_f32 v[12:13], v[12:13], v[92:93], v[14:15]
	s_nop 0
	v_cvt_pk_bf16_f32 v16, v12, v13
	global_store_dword v64, v16, s[68:69]
	v_lshlrev_b32_e32 v14, 16, v77
	v_and_b32_e32 v15, 0xffff0000, v77
	v_pk_fma_f32 v[12:13], v[12:13], v[94:95], v[14:15]
	s_nop 0
	v_cvt_pk_bf16_f32 v16, v12, v13
	global_store_dword v65, v16, s[68:69]
	v_lshlrev_b32_e32 v14, 16, v78
	v_and_b32_e32 v15, 0xffff0000, v78
	v_pk_fma_f32 v[12:13], v[12:13], v[96:97], v[14:15]
	s_nop 0
	v_cvt_pk_bf16_f32 v16, v12, v13
	global_store_dword v66, v16, s[68:69]
	v_lshlrev_b32_e32 v14, 16, v79
	v_and_b32_e32 v15, 0xffff0000, v79
	v_pk_fma_f32 v[12:13], v[12:13], v[98:99], v[14:15]
	s_nop 0
	v_cvt_pk_bf16_f32 v16, v12, v13
	global_store_dword v67, v16, s[68:69]
	v_lshlrev_b32_e32 v14, 16, v80
	v_and_b32_e32 v15, 0xffff0000, v80
	v_pk_fma_f32 v[12:13], v[12:13], v[100:101], v[14:15]
	s_nop 0
	v_cvt_pk_bf16_f32 v16, v12, v13
	global_store_dword v68, v16, s[68:69]
	v_lshlrev_b32_e32 v14, 16, v81
	v_and_b32_e32 v15, 0xffff0000, v81
	v_pk_fma_f32 v[12:13], v[12:13], v[102:103], v[14:15]
	s_nop 0
	v_cvt_pk_bf16_f32 v16, v12, v13
	global_store_dword v69, v16, s[68:69]
	v_lshlrev_b32_e32 v14, 16, v82
	v_and_b32_e32 v15, 0xffff0000, v82
	v_pk_fma_f32 v[12:13], v[12:13], v[104:105], v[14:15]
	s_nop 0
	v_cvt_pk_bf16_f32 v16, v12, v13
	global_store_dword v70, v16, s[68:69]
	v_lshlrev_b32_e32 v14, 16, v83
	v_and_b32_e32 v15, 0xffff0000, v83
	v_pk_fma_f32 v[12:13], v[12:13], v[106:107], v[14:15]
	s_nop 0
	v_cvt_pk_bf16_f32 v16, v12, v13
	global_store_dword v71, v16, s[68:69]
	v_lshlrev_b32_e32 v14, 16, v84
	v_and_b32_e32 v15, 0xffff0000, v84
	v_pk_fma_f32 v[12:13], v[12:13], v[108:109], v[14:15]
	s_nop 0
	v_cvt_pk_bf16_f32 v16, v12, v13
	global_store_dword v72, v16, s[68:69]
	v_lshlrev_b32_e32 v14, 16, v85
	v_and_b32_e32 v15, 0xffff0000, v85
	v_pk_fma_f32 v[12:13], v[12:13], v[110:111], v[14:15]
	v_add_u32_e32 v60, 0x68000, v2
	global_load_dword v73, v60, s[68:69]
	v_add_u32_e32 v61, 0x6c000, v2
	global_load_dword v74, v61, s[68:69]
	v_add_u32_e32 v62, 0x70000, v2
	global_load_dword v75, v62, s[68:69]
	v_add_u32_e32 v63, 0x74000, v2
	global_load_dword v76, v63, s[68:69]
	v_add_u32_e32 v64, 0x78000, v2
	global_load_dword v77, v64, s[68:69]
	v_add_u32_e32 v65, 0x7c000, v2
	global_load_dword v78, v65, s[68:69]
	v_add_u32_e32 v66, 0x80000, v2
	global_load_dword v79, v66, s[68:69]
	v_add_u32_e32 v67, 0x84000, v2
	global_load_dword v80, v67, s[68:69]
	v_add_u32_e32 v68, 0x88000, v2
	global_load_dword v81, v68, s[68:69]
	v_add_u32_e32 v69, 0x8c000, v2
	global_load_dword v82, v69, s[68:69]
	v_add_u32_e32 v70, 0x90000, v2
	global_load_dword v83, v70, s[68:69]
	v_add_u32_e32 v71, 0x94000, v2
	global_load_dword v84, v71, s[68:69]
	v_add_u32_e32 v72, 0x98000, v2
	global_load_dword v85, v72, s[68:69]
	v_add_u32_e32 v164, 0x1a00, v4
	global_load_dwordx2 v[86:87], v164, s[70:71] offset:0
	global_load_dwordx2 v[88:89], v164, s[70:71] offset:256
	global_load_dwordx2 v[90:91], v164, s[70:71] offset:512
	global_load_dwordx2 v[92:93], v164, s[70:71] offset:768
	global_load_dwordx2 v[94:95], v164, s[70:71] offset:1024
	global_load_dwordx2 v[96:97], v164, s[70:71] offset:1280
	global_load_dwordx2 v[98:99], v164, s[70:71] offset:1536
	global_load_dwordx2 v[100:101], v164, s[70:71] offset:1792
	global_load_dwordx2 v[102:103], v164, s[70:71] offset:2048
	global_load_dwordx2 v[104:105], v164, s[70:71] offset:2304
	global_load_dwordx2 v[106:107], v164, s[70:71] offset:2560
	global_load_dwordx2 v[108:109], v164, s[70:71] offset:2816
	global_load_dwordx2 v[110:111], v164, s[70:71] offset:3072
	s_waitcnt vmcnt(39)
	s_nop 0
	v_cvt_pk_bf16_f32 v16, v12, v13
	global_store_dword v112, v16, s[68:69]
	v_lshlrev_b32_e32 v14, 16, v125
	v_and_b32_e32 v15, 0xffff0000, v125
	v_pk_fma_f32 v[12:13], v[12:13], v[138:139], v[14:15]
	s_nop 0
	v_cvt_pk_bf16_f32 v16, v12, v13
	global_store_dword v113, v16, s[68:69]
	v_lshlrev_b32_e32 v14, 16, v126
	v_and_b32_e32 v15, 0xffff0000, v126
	v_pk_fma_f32 v[12:13], v[12:13], v[140:141], v[14:15]
	s_nop 0
	v_cvt_pk_bf16_f32 v16, v12, v13
	global_store_dword v114, v16, s[68:69]
	v_lshlrev_b32_e32 v14, 16, v127
	v_and_b32_e32 v15, 0xffff0000, v127
	v_pk_fma_f32 v[12:13], v[12:13], v[142:143], v[14:15]
	s_nop 0
	v_cvt_pk_bf16_f32 v16, v12, v13
	global_store_dword v115, v16, s[68:69]
	v_lshlrev_b32_e32 v14, 16, v128
	v_and_b32_e32 v15, 0xffff0000, v128
	v_pk_fma_f32 v[12:13], v[12:13], v[144:145], v[14:15]
	s_nop 0
	v_cvt_pk_bf16_f32 v16, v12, v13
	global_store_dword v116, v16, s[68:69]
	v_lshlrev_b32_e32 v14, 16, v129
	v_and_b32_e32 v15, 0xffff0000, v129
	v_pk_fma_f32 v[12:13], v[12:13], v[146:147], v[14:15]
	s_nop 0
	v_cvt_pk_bf16_f32 v16, v12, v13
	global_store_dword v117, v16, s[68:69]
	v_lshlrev_b32_e32 v14, 16, v130
	v_and_b32_e32 v15, 0xffff0000, v130
	v_pk_fma_f32 v[12:13], v[12:13], v[148:149], v[14:15]
	s_nop 0
	v_cvt_pk_bf16_f32 v16, v12, v13
	global_store_dword v118, v16, s[68:69]
	v_lshlrev_b32_e32 v14, 16, v131
	v_and_b32_e32 v15, 0xffff0000, v131
	v_pk_fma_f32 v[12:13], v[12:13], v[150:151], v[14:15]
	s_nop 0
	v_cvt_pk_bf16_f32 v16, v12, v13
	global_store_dword v119, v16, s[68:69]
	v_lshlrev_b32_e32 v14, 16, v132
	v_and_b32_e32 v15, 0xffff0000, v132
	v_pk_fma_f32 v[12:13], v[12:13], v[152:153], v[14:15]
	s_nop 0
	v_cvt_pk_bf16_f32 v16, v12, v13
	global_store_dword v120, v16, s[68:69]
	v_lshlrev_b32_e32 v14, 16, v133
	v_and_b32_e32 v15, 0xffff0000, v133
	v_pk_fma_f32 v[12:13], v[12:13], v[154:155], v[14:15]
	s_nop 0
	v_cvt_pk_bf16_f32 v16, v12, v13
	global_store_dword v121, v16, s[68:69]
	v_lshlrev_b32_e32 v14, 16, v134
	v_and_b32_e32 v15, 0xffff0000, v134
	v_pk_fma_f32 v[12:13], v[12:13], v[156:157], v[14:15]
	s_nop 0
	v_cvt_pk_bf16_f32 v16, v12, v13
	global_store_dword v122, v16, s[68:69]
	v_lshlrev_b32_e32 v14, 16, v135
	v_and_b32_e32 v15, 0xffff0000, v135
	v_pk_fma_f32 v[12:13], v[12:13], v[158:159], v[14:15]
	s_nop 0
	v_cvt_pk_bf16_f32 v16, v12, v13
	global_store_dword v123, v16, s[68:69]
	v_lshlrev_b32_e32 v14, 16, v136
	v_and_b32_e32 v15, 0xffff0000, v136
	v_pk_fma_f32 v[12:13], v[12:13], v[160:161], v[14:15]
	s_nop 0
	v_cvt_pk_bf16_f32 v16, v12, v13
	global_store_dword v124, v16, s[68:69]
	v_lshlrev_b32_e32 v14, 16, v137
	v_and_b32_e32 v15, 0xffff0000, v137
	v_pk_fma_f32 v[12:13], v[12:13], v[162:163], v[14:15]
	v_add_u32_e32 v112, 0x9c000, v2
	global_load_dword v125, v112, s[68:69]
	v_add_u32_e32 v113, 0xa0000, v2
	global_load_dword v126, v113, s[68:69]
	v_add_u32_e32 v114, 0xa4000, v2
	global_load_dword v127, v114, s[68:69]
	v_add_u32_e32 v115, 0xa8000, v2
	global_load_dword v128, v115, s[68:69]
	v_add_u32_e32 v116, 0xac000, v2
	global_load_dword v129, v116, s[68:69]
	v_add_u32_e32 v117, 0xb0000, v2
	global_load_dword v130, v117, s[68:69]
	v_add_u32_e32 v118, 0xb4000, v2
	global_load_dword v131, v118, s[68:69]
	v_add_u32_e32 v119, 0xb8000, v2
	global_load_dword v132, v119, s[68:69]
	v_add_u32_e32 v120, 0xbc000, v2
	global_load_dword v133, v120, s[68:69]
	v_add_u32_e32 v121, 0xc0000, v2
	global_load_dword v134, v121, s[68:69]
	v_add_u32_e32 v122, 0xc4000, v2
	global_load_dword v135, v122, s[68:69]
	v_add_u32_e32 v123, 0xc8000, v2
	global_load_dword v136, v123, s[68:69]
	v_add_u32_e32 v124, 0xcc000, v2
	global_load_dword v137, v124, s[68:69]
	v_add_u32_e32 v165, 0x2700, v4
	global_load_dwordx2 v[138:139], v165, s[70:71] offset:0
	global_load_dwordx2 v[140:141], v165, s[70:71] offset:256
	global_load_dwordx2 v[142:143], v165, s[70:71] offset:512
	global_load_dwordx2 v[144:145], v165, s[70:71] offset:768
	global_load_dwordx2 v[146:147], v165, s[70:71] offset:1024
	global_load_dwordx2 v[148:149], v165, s[70:71] offset:1280
	global_load_dwordx2 v[150:151], v165, s[70:71] offset:1536
	global_load_dwordx2 v[152:153], v165, s[70:71] offset:1792
	global_load_dwordx2 v[154:155], v165, s[70:71] offset:2048
	global_load_dwordx2 v[156:157], v165, s[70:71] offset:2304
	global_load_dwordx2 v[158:159], v165, s[70:71] offset:2560
	global_load_dwordx2 v[160:161], v165, s[70:71] offset:2816
	global_load_dwordx2 v[162:163], v165, s[70:71] offset:3072
	s_waitcnt vmcnt(39)
	s_nop 0
	v_cvt_pk_bf16_f32 v16, v12, v13
	global_store_dword v60, v16, s[68:69]
	v_lshlrev_b32_e32 v14, 16, v73
	v_and_b32_e32 v15, 0xffff0000, v73
	v_pk_fma_f32 v[12:13], v[12:13], v[86:87], v[14:15]
	s_nop 0
	v_cvt_pk_bf16_f32 v16, v12, v13
	global_store_dword v61, v16, s[68:69]
	v_lshlrev_b32_e32 v14, 16, v74
	v_and_b32_e32 v15, 0xffff0000, v74
	v_pk_fma_f32 v[12:13], v[12:13], v[88:89], v[14:15]
	s_nop 0
	v_cvt_pk_bf16_f32 v16, v12, v13
	global_store_dword v62, v16, s[68:69]
	v_lshlrev_b32_e32 v14, 16, v75
	v_and_b32_e32 v15, 0xffff0000, v75
	v_pk_fma_f32 v[12:13], v[12:13], v[90:91], v[14:15]
	s_nop 0
	v_cvt_pk_bf16_f32 v16, v12, v13
	global_store_dword v63, v16, s[68:69]
	v_lshlrev_b32_e32 v14, 16, v76
	v_and_b32_e32 v15, 0xffff0000, v76
	v_pk_fma_f32 v[12:13], v[12:13], v[92:93], v[14:15]
	s_nop 0
	v_cvt_pk_bf16_f32 v16, v12, v13
	global_store_dword v64, v16, s[68:69]
	v_lshlrev_b32_e32 v14, 16, v77
	v_and_b32_e32 v15, 0xffff0000, v77
	v_pk_fma_f32 v[12:13], v[12:13], v[94:95], v[14:15]
	s_nop 0
	v_cvt_pk_bf16_f32 v16, v12, v13
	global_store_dword v65, v16, s[68:69]
	v_lshlrev_b32_e32 v14, 16, v78
	v_and_b32_e32 v15, 0xffff0000, v78
	v_pk_fma_f32 v[12:13], v[12:13], v[96:97], v[14:15]
	s_nop 0
	v_cvt_pk_bf16_f32 v16, v12, v13
	global_store_dword v66, v16, s[68:69]
	v_lshlrev_b32_e32 v14, 16, v79
	v_and_b32_e32 v15, 0xffff0000, v79
	v_pk_fma_f32 v[12:13], v[12:13], v[98:99], v[14:15]
	s_nop 0
	v_cvt_pk_bf16_f32 v16, v12, v13
	global_store_dword v67, v16, s[68:69]
	v_lshlrev_b32_e32 v14, 16, v80
	v_and_b32_e32 v15, 0xffff0000, v80
	v_pk_fma_f32 v[12:13], v[12:13], v[100:101], v[14:15]
	s_nop 0
	v_cvt_pk_bf16_f32 v16, v12, v13
	global_store_dword v68, v16, s[68:69]
	v_lshlrev_b32_e32 v14, 16, v81
	v_and_b32_e32 v15, 0xffff0000, v81
	v_pk_fma_f32 v[12:13], v[12:13], v[102:103], v[14:15]
	s_nop 0
	v_cvt_pk_bf16_f32 v16, v12, v13
	global_store_dword v69, v16, s[68:69]
	v_lshlrev_b32_e32 v14, 16, v82
	v_and_b32_e32 v15, 0xffff0000, v82
	v_pk_fma_f32 v[12:13], v[12:13], v[104:105], v[14:15]
	s_nop 0
	v_cvt_pk_bf16_f32 v16, v12, v13
	global_store_dword v70, v16, s[68:69]
	v_lshlrev_b32_e32 v14, 16, v83
	v_and_b32_e32 v15, 0xffff0000, v83
	v_pk_fma_f32 v[12:13], v[12:13], v[106:107], v[14:15]
	s_nop 0
	v_cvt_pk_bf16_f32 v16, v12, v13
	global_store_dword v71, v16, s[68:69]
	v_lshlrev_b32_e32 v14, 16, v84
	v_and_b32_e32 v15, 0xffff0000, v84
	v_pk_fma_f32 v[12:13], v[12:13], v[108:109], v[14:15]
	s_nop 0
	v_cvt_pk_bf16_f32 v16, v12, v13
	global_store_dword v72, v16, s[68:69]
	v_lshlrev_b32_e32 v14, 16, v85
	v_and_b32_e32 v15, 0xffff0000, v85
	v_pk_fma_f32 v[12:13], v[12:13], v[110:111], v[14:15]
	v_add_u32_e32 v60, 0xd0000, v2
	global_load_dword v73, v60, s[68:69]
	v_add_u32_e32 v61, 0xd4000, v2
	global_load_dword v74, v61, s[68:69]
	v_add_u32_e32 v62, 0xd8000, v2
	global_load_dword v75, v62, s[68:69]
	v_add_u32_e32 v63, 0xdc000, v2
	global_load_dword v76, v63, s[68:69]
	v_add_u32_e32 v64, 0xe0000, v2
	global_load_dword v77, v64, s[68:69]
	v_add_u32_e32 v65, 0xe4000, v2
	global_load_dword v78, v65, s[68:69]
	v_add_u32_e32 v66, 0xe8000, v2
	global_load_dword v79, v66, s[68:69]
	v_add_u32_e32 v67, 0xec000, v2
	global_load_dword v80, v67, s[68:69]
	v_add_u32_e32 v68, 0xf0000, v2
	global_load_dword v81, v68, s[68:69]
	v_add_u32_e32 v69, 0xf4000, v2
	global_load_dword v82, v69, s[68:69]
	v_add_u32_e32 v70, 0xf8000, v2
	global_load_dword v83, v70, s[68:69]
	v_add_u32_e32 v71, 0xfc000, v2
	global_load_dword v84, v71, s[68:69]
	v_add_u32_e32 v72, 0x100000, v2
	global_load_dword v85, v72, s[68:69]
	v_add_u32_e32 v164, 0x3400, v4
	global_load_dwordx2 v[86:87], v164, s[70:71] offset:0
	global_load_dwordx2 v[88:89], v164, s[70:71] offset:256
	global_load_dwordx2 v[90:91], v164, s[70:71] offset:512
	global_load_dwordx2 v[92:93], v164, s[70:71] offset:768
	global_load_dwordx2 v[94:95], v164, s[70:71] offset:1024
	global_load_dwordx2 v[96:97], v164, s[70:71] offset:1280
	global_load_dwordx2 v[98:99], v164, s[70:71] offset:1536
	global_load_dwordx2 v[100:101], v164, s[70:71] offset:1792
	global_load_dwordx2 v[102:103], v164, s[70:71] offset:2048
	global_load_dwordx2 v[104:105], v164, s[70:71] offset:2304
	global_load_dwordx2 v[106:107], v164, s[70:71] offset:2560
	global_load_dwordx2 v[108:109], v164, s[70:71] offset:2816
	global_load_dwordx2 v[110:111], v164, s[70:71] offset:3072
	s_waitcnt vmcnt(39)
	s_nop 0
	v_cvt_pk_bf16_f32 v16, v12, v13
	global_store_dword v112, v16, s[68:69]
	v_lshlrev_b32_e32 v14, 16, v125
	v_and_b32_e32 v15, 0xffff0000, v125
	v_pk_fma_f32 v[12:13], v[12:13], v[138:139], v[14:15]
	s_nop 0
	v_cvt_pk_bf16_f32 v16, v12, v13
	global_store_dword v113, v16, s[68:69]
	v_lshlrev_b32_e32 v14, 16, v126
	v_and_b32_e32 v15, 0xffff0000, v126
	v_pk_fma_f32 v[12:13], v[12:13], v[140:141], v[14:15]
	s_nop 0
	v_cvt_pk_bf16_f32 v16, v12, v13
	global_store_dword v114, v16, s[68:69]
	v_lshlrev_b32_e32 v14, 16, v127
	v_and_b32_e32 v15, 0xffff0000, v127
	v_pk_fma_f32 v[12:13], v[12:13], v[142:143], v[14:15]
	s_nop 0
	v_cvt_pk_bf16_f32 v16, v12, v13
	global_store_dword v115, v16, s[68:69]
	v_lshlrev_b32_e32 v14, 16, v128
	v_and_b32_e32 v15, 0xffff0000, v128
	v_pk_fma_f32 v[12:13], v[12:13], v[144:145], v[14:15]
	s_nop 0
	v_cvt_pk_bf16_f32 v16, v12, v13
	global_store_dword v116, v16, s[68:69]
	v_lshlrev_b32_e32 v14, 16, v129
	v_and_b32_e32 v15, 0xffff0000, v129
	v_pk_fma_f32 v[12:13], v[12:13], v[146:147], v[14:15]
	s_nop 0
	v_cvt_pk_bf16_f32 v16, v12, v13
	global_store_dword v117, v16, s[68:69]
	v_lshlrev_b32_e32 v14, 16, v130
	v_and_b32_e32 v15, 0xffff0000, v130
	v_pk_fma_f32 v[12:13], v[12:13], v[148:149], v[14:15]
	s_nop 0
	v_cvt_pk_bf16_f32 v16, v12, v13
	global_store_dword v118, v16, s[68:69]
	v_lshlrev_b32_e32 v14, 16, v131
	v_and_b32_e32 v15, 0xffff0000, v131
	v_pk_fma_f32 v[12:13], v[12:13], v[150:151], v[14:15]
	s_nop 0
	v_cvt_pk_bf16_f32 v16, v12, v13
	global_store_dword v119, v16, s[68:69]
	v_lshlrev_b32_e32 v14, 16, v132
	v_and_b32_e32 v15, 0xffff0000, v132
	v_pk_fma_f32 v[12:13], v[12:13], v[152:153], v[14:15]
	s_nop 0
	v_cvt_pk_bf16_f32 v16, v12, v13
	global_store_dword v120, v16, s[68:69]
	v_lshlrev_b32_e32 v14, 16, v133
	v_and_b32_e32 v15, 0xffff0000, v133
	v_pk_fma_f32 v[12:13], v[12:13], v[154:155], v[14:15]
	s_nop 0
	v_cvt_pk_bf16_f32 v16, v12, v13
	global_store_dword v121, v16, s[68:69]
	v_lshlrev_b32_e32 v14, 16, v134
	v_and_b32_e32 v15, 0xffff0000, v134
	v_pk_fma_f32 v[12:13], v[12:13], v[156:157], v[14:15]
	s_nop 0
	v_cvt_pk_bf16_f32 v16, v12, v13
	global_store_dword v122, v16, s[68:69]
	v_lshlrev_b32_e32 v14, 16, v135
	v_and_b32_e32 v15, 0xffff0000, v135
	v_pk_fma_f32 v[12:13], v[12:13], v[158:159], v[14:15]
	s_nop 0
	v_cvt_pk_bf16_f32 v16, v12, v13
	global_store_dword v123, v16, s[68:69]
	v_lshlrev_b32_e32 v14, 16, v136
	v_and_b32_e32 v15, 0xffff0000, v136
	v_pk_fma_f32 v[12:13], v[12:13], v[160:161], v[14:15]
	s_nop 0
	v_cvt_pk_bf16_f32 v16, v12, v13
	global_store_dword v124, v16, s[68:69]
	v_lshlrev_b32_e32 v14, 16, v137
	v_and_b32_e32 v15, 0xffff0000, v137
	v_pk_fma_f32 v[12:13], v[12:13], v[162:163], v[14:15]
	v_add_u32_e32 v112, 0x104000, v2
	global_load_dword v125, v112, s[68:69]
	v_add_u32_e32 v113, 0x108000, v2
	global_load_dword v126, v113, s[68:69]
	v_add_u32_e32 v114, 0x10c000, v2
	global_load_dword v127, v114, s[68:69]
	v_add_u32_e32 v115, 0x110000, v2
	global_load_dword v128, v115, s[68:69]
	v_add_u32_e32 v116, 0x114000, v2
	global_load_dword v129, v116, s[68:69]
	v_add_u32_e32 v117, 0x118000, v2
	global_load_dword v130, v117, s[68:69]
	v_add_u32_e32 v118, 0x11c000, v2
	global_load_dword v131, v118, s[68:69]
	v_add_u32_e32 v119, 0x120000, v2
	global_load_dword v132, v119, s[68:69]
	v_add_u32_e32 v120, 0x124000, v2
	global_load_dword v133, v120, s[68:69]
	v_add_u32_e32 v121, 0x128000, v2
	global_load_dword v134, v121, s[68:69]
	v_add_u32_e32 v122, 0x12c000, v2
	global_load_dword v135, v122, s[68:69]
	v_add_u32_e32 v123, 0x130000, v2
	global_load_dword v136, v123, s[68:69]
	v_add_u32_e32 v124, 0x134000, v2
	global_load_dword v137, v124, s[68:69]
	v_add_u32_e32 v165, 0x4100, v4
	global_load_dwordx2 v[138:139], v165, s[70:71] offset:0
	global_load_dwordx2 v[140:141], v165, s[70:71] offset:256
	global_load_dwordx2 v[142:143], v165, s[70:71] offset:512
	global_load_dwordx2 v[144:145], v165, s[70:71] offset:768
	global_load_dwordx2 v[146:147], v165, s[70:71] offset:1024
	global_load_dwordx2 v[148:149], v165, s[70:71] offset:1280
	global_load_dwordx2 v[150:151], v165, s[70:71] offset:1536
	global_load_dwordx2 v[152:153], v165, s[70:71] offset:1792
	global_load_dwordx2 v[154:155], v165, s[70:71] offset:2048
	global_load_dwordx2 v[156:157], v165, s[70:71] offset:2304
	global_load_dwordx2 v[158:159], v165, s[70:71] offset:2560
	global_load_dwordx2 v[160:161], v165, s[70:71] offset:2816
	global_load_dwordx2 v[162:163], v165, s[70:71] offset:3072
	s_waitcnt vmcnt(39)
	s_nop 0
	v_cvt_pk_bf16_f32 v16, v12, v13
	global_store_dword v60, v16, s[68:69]
	v_lshlrev_b32_e32 v14, 16, v73
	v_and_b32_e32 v15, 0xffff0000, v73
	v_pk_fma_f32 v[12:13], v[12:13], v[86:87], v[14:15]
	s_nop 0
	v_cvt_pk_bf16_f32 v16, v12, v13
	global_store_dword v61, v16, s[68:69]
	v_lshlrev_b32_e32 v14, 16, v74
	v_and_b32_e32 v15, 0xffff0000, v74
	v_pk_fma_f32 v[12:13], v[12:13], v[88:89], v[14:15]
	s_nop 0
	v_cvt_pk_bf16_f32 v16, v12, v13
	global_store_dword v62, v16, s[68:69]
	v_lshlrev_b32_e32 v14, 16, v75
	v_and_b32_e32 v15, 0xffff0000, v75
	v_pk_fma_f32 v[12:13], v[12:13], v[90:91], v[14:15]
	s_nop 0
	v_cvt_pk_bf16_f32 v16, v12, v13
	global_store_dword v63, v16, s[68:69]
	v_lshlrev_b32_e32 v14, 16, v76
	v_and_b32_e32 v15, 0xffff0000, v76
	v_pk_fma_f32 v[12:13], v[12:13], v[92:93], v[14:15]
	s_nop 0
	v_cvt_pk_bf16_f32 v16, v12, v13
	global_store_dword v64, v16, s[68:69]
	v_lshlrev_b32_e32 v14, 16, v77
	v_and_b32_e32 v15, 0xffff0000, v77
	v_pk_fma_f32 v[12:13], v[12:13], v[94:95], v[14:15]
	s_nop 0
	v_cvt_pk_bf16_f32 v16, v12, v13
	global_store_dword v65, v16, s[68:69]
	v_lshlrev_b32_e32 v14, 16, v78
	v_and_b32_e32 v15, 0xffff0000, v78
	v_pk_fma_f32 v[12:13], v[12:13], v[96:97], v[14:15]
	s_nop 0
	v_cvt_pk_bf16_f32 v16, v12, v13
	global_store_dword v66, v16, s[68:69]
	v_lshlrev_b32_e32 v14, 16, v79
	v_and_b32_e32 v15, 0xffff0000, v79
	v_pk_fma_f32 v[12:13], v[12:13], v[98:99], v[14:15]
	s_nop 0
	v_cvt_pk_bf16_f32 v16, v12, v13
	global_store_dword v67, v16, s[68:69]
	v_lshlrev_b32_e32 v14, 16, v80
	v_and_b32_e32 v15, 0xffff0000, v80
	v_pk_fma_f32 v[12:13], v[12:13], v[100:101], v[14:15]
	s_nop 0
	v_cvt_pk_bf16_f32 v16, v12, v13
	global_store_dword v68, v16, s[68:69]
	v_lshlrev_b32_e32 v14, 16, v81
	v_and_b32_e32 v15, 0xffff0000, v81
	v_pk_fma_f32 v[12:13], v[12:13], v[102:103], v[14:15]
	s_nop 0
	v_cvt_pk_bf16_f32 v16, v12, v13
	global_store_dword v69, v16, s[68:69]
	v_lshlrev_b32_e32 v14, 16, v82
	v_and_b32_e32 v15, 0xffff0000, v82
	v_pk_fma_f32 v[12:13], v[12:13], v[104:105], v[14:15]
	s_nop 0
	v_cvt_pk_bf16_f32 v16, v12, v13
	global_store_dword v70, v16, s[68:69]
	v_lshlrev_b32_e32 v14, 16, v83
	v_and_b32_e32 v15, 0xffff0000, v83
	v_pk_fma_f32 v[12:13], v[12:13], v[106:107], v[14:15]
	s_nop 0
	v_cvt_pk_bf16_f32 v16, v12, v13
	global_store_dword v71, v16, s[68:69]
	v_lshlrev_b32_e32 v14, 16, v84
	v_and_b32_e32 v15, 0xffff0000, v84
	v_pk_fma_f32 v[12:13], v[12:13], v[108:109], v[14:15]
	s_nop 0
	v_cvt_pk_bf16_f32 v16, v12, v13
	global_store_dword v72, v16, s[68:69]
	v_lshlrev_b32_e32 v14, 16, v85
	v_and_b32_e32 v15, 0xffff0000, v85
	v_pk_fma_f32 v[12:13], v[12:13], v[110:111], v[14:15]
	v_add_u32_e32 v60, 0x138000, v2
	global_load_dword v73, v60, s[68:69]
	v_add_u32_e32 v61, 0x13c000, v2
	global_load_dword v74, v61, s[68:69]
	v_add_u32_e32 v62, 0x140000, v2
	global_load_dword v75, v62, s[68:69]
	v_add_u32_e32 v63, 0x144000, v2
	global_load_dword v76, v63, s[68:69]
	v_add_u32_e32 v64, 0x148000, v2
	global_load_dword v77, v64, s[68:69]
	v_add_u32_e32 v65, 0x14c000, v2
	global_load_dword v78, v65, s[68:69]
	v_add_u32_e32 v66, 0x150000, v2
	global_load_dword v79, v66, s[68:69]
	v_add_u32_e32 v67, 0x154000, v2
	global_load_dword v80, v67, s[68:69]
	v_add_u32_e32 v68, 0x158000, v2
	global_load_dword v81, v68, s[68:69]
	v_add_u32_e32 v69, 0x15c000, v2
	global_load_dword v82, v69, s[68:69]
	v_add_u32_e32 v70, 0x160000, v2
	global_load_dword v83, v70, s[68:69]
	v_add_u32_e32 v71, 0x164000, v2
	global_load_dword v84, v71, s[68:69]
	v_add_u32_e32 v72, 0x168000, v2
	global_load_dword v85, v72, s[68:69]
	v_add_u32_e32 v164, 0x4e00, v4
	global_load_dwordx2 v[86:87], v164, s[70:71] offset:0
	global_load_dwordx2 v[88:89], v164, s[70:71] offset:256
	global_load_dwordx2 v[90:91], v164, s[70:71] offset:512
	global_load_dwordx2 v[92:93], v164, s[70:71] offset:768
	global_load_dwordx2 v[94:95], v164, s[70:71] offset:1024
	global_load_dwordx2 v[96:97], v164, s[70:71] offset:1280
	global_load_dwordx2 v[98:99], v164, s[70:71] offset:1536
	global_load_dwordx2 v[100:101], v164, s[70:71] offset:1792
	global_load_dwordx2 v[102:103], v164, s[70:71] offset:2048
	global_load_dwordx2 v[104:105], v164, s[70:71] offset:2304
	global_load_dwordx2 v[106:107], v164, s[70:71] offset:2560
	global_load_dwordx2 v[108:109], v164, s[70:71] offset:2816
	global_load_dwordx2 v[110:111], v164, s[70:71] offset:3072
	s_waitcnt vmcnt(39)
	s_nop 0
	v_cvt_pk_bf16_f32 v16, v12, v13
	global_store_dword v112, v16, s[68:69]
	v_lshlrev_b32_e32 v14, 16, v125
	v_and_b32_e32 v15, 0xffff0000, v125
	v_pk_fma_f32 v[12:13], v[12:13], v[138:139], v[14:15]
	s_nop 0
	v_cvt_pk_bf16_f32 v16, v12, v13
	global_store_dword v113, v16, s[68:69]
	v_lshlrev_b32_e32 v14, 16, v126
	v_and_b32_e32 v15, 0xffff0000, v126
	v_pk_fma_f32 v[12:13], v[12:13], v[140:141], v[14:15]
	s_nop 0
	v_cvt_pk_bf16_f32 v16, v12, v13
	global_store_dword v114, v16, s[68:69]
	v_lshlrev_b32_e32 v14, 16, v127
	v_and_b32_e32 v15, 0xffff0000, v127
	v_pk_fma_f32 v[12:13], v[12:13], v[142:143], v[14:15]
	s_nop 0
	v_cvt_pk_bf16_f32 v16, v12, v13
	global_store_dword v115, v16, s[68:69]
	v_lshlrev_b32_e32 v14, 16, v128
	v_and_b32_e32 v15, 0xffff0000, v128
	v_pk_fma_f32 v[12:13], v[12:13], v[144:145], v[14:15]
	s_nop 0
	v_cvt_pk_bf16_f32 v16, v12, v13
	global_store_dword v116, v16, s[68:69]
	v_lshlrev_b32_e32 v14, 16, v129
	v_and_b32_e32 v15, 0xffff0000, v129
	v_pk_fma_f32 v[12:13], v[12:13], v[146:147], v[14:15]
	s_nop 0
	v_cvt_pk_bf16_f32 v16, v12, v13
	global_store_dword v117, v16, s[68:69]
	v_lshlrev_b32_e32 v14, 16, v130
	v_and_b32_e32 v15, 0xffff0000, v130
	v_pk_fma_f32 v[12:13], v[12:13], v[148:149], v[14:15]
	s_nop 0
	v_cvt_pk_bf16_f32 v16, v12, v13
	global_store_dword v118, v16, s[68:69]
	v_lshlrev_b32_e32 v14, 16, v131
	v_and_b32_e32 v15, 0xffff0000, v131
	v_pk_fma_f32 v[12:13], v[12:13], v[150:151], v[14:15]
	s_nop 0
	v_cvt_pk_bf16_f32 v16, v12, v13
	global_store_dword v119, v16, s[68:69]
	v_lshlrev_b32_e32 v14, 16, v132
	v_and_b32_e32 v15, 0xffff0000, v132
	v_pk_fma_f32 v[12:13], v[12:13], v[152:153], v[14:15]
	s_nop 0
	v_cvt_pk_bf16_f32 v16, v12, v13
	global_store_dword v120, v16, s[68:69]
	v_lshlrev_b32_e32 v14, 16, v133
	v_and_b32_e32 v15, 0xffff0000, v133
	v_pk_fma_f32 v[12:13], v[12:13], v[154:155], v[14:15]
	s_nop 0
	v_cvt_pk_bf16_f32 v16, v12, v13
	global_store_dword v121, v16, s[68:69]
	v_lshlrev_b32_e32 v14, 16, v134
	v_and_b32_e32 v15, 0xffff0000, v134
	v_pk_fma_f32 v[12:13], v[12:13], v[156:157], v[14:15]
	s_nop 0
	v_cvt_pk_bf16_f32 v16, v12, v13
	global_store_dword v122, v16, s[68:69]
	v_lshlrev_b32_e32 v14, 16, v135
	v_and_b32_e32 v15, 0xffff0000, v135
	v_pk_fma_f32 v[12:13], v[12:13], v[158:159], v[14:15]
	s_nop 0
	v_cvt_pk_bf16_f32 v16, v12, v13
	global_store_dword v123, v16, s[68:69]
	v_lshlrev_b32_e32 v14, 16, v136
	v_and_b32_e32 v15, 0xffff0000, v136
	v_pk_fma_f32 v[12:13], v[12:13], v[160:161], v[14:15]
	s_nop 0
	v_cvt_pk_bf16_f32 v16, v12, v13
	global_store_dword v124, v16, s[68:69]
	v_lshlrev_b32_e32 v14, 16, v137
	v_and_b32_e32 v15, 0xffff0000, v137
	v_pk_fma_f32 v[12:13], v[12:13], v[162:163], v[14:15]
	v_add_u32_e32 v112, 0x16c000, v2
	global_load_dword v125, v112, s[68:69]
	v_add_u32_e32 v113, 0x170000, v2
	global_load_dword v126, v113, s[68:69]
	v_add_u32_e32 v114, 0x174000, v2
	global_load_dword v127, v114, s[68:69]
	v_add_u32_e32 v115, 0x178000, v2
	global_load_dword v128, v115, s[68:69]
	v_add_u32_e32 v116, 0x17c000, v2
	global_load_dword v129, v116, s[68:69]
	v_add_u32_e32 v117, 0x180000, v2
	global_load_dword v130, v117, s[68:69]
	v_add_u32_e32 v118, 0x184000, v2
	global_load_dword v131, v118, s[68:69]
	v_add_u32_e32 v119, 0x188000, v2
	global_load_dword v132, v119, s[68:69]
	v_add_u32_e32 v120, 0x18c000, v2
	global_load_dword v133, v120, s[68:69]
	v_add_u32_e32 v121, 0x190000, v2
	global_load_dword v134, v121, s[68:69]
	v_add_u32_e32 v122, 0x194000, v2
	global_load_dword v135, v122, s[68:69]
	v_add_u32_e32 v123, 0x198000, v2
	global_load_dword v136, v123, s[68:69]
	v_add_u32_e32 v124, 0x19c000, v2
	global_load_dword v137, v124, s[68:69]
	v_add_u32_e32 v165, 0x5b00, v4
	global_load_dwordx2 v[138:139], v165, s[70:71] offset:0
	global_load_dwordx2 v[140:141], v165, s[70:71] offset:256
	global_load_dwordx2 v[142:143], v165, s[70:71] offset:512
	global_load_dwordx2 v[144:145], v165, s[70:71] offset:768
	global_load_dwordx2 v[146:147], v165, s[70:71] offset:1024
	global_load_dwordx2 v[148:149], v165, s[70:71] offset:1280
	global_load_dwordx2 v[150:151], v165, s[70:71] offset:1536
	global_load_dwordx2 v[152:153], v165, s[70:71] offset:1792
	global_load_dwordx2 v[154:155], v165, s[70:71] offset:2048
	global_load_dwordx2 v[156:157], v165, s[70:71] offset:2304
	global_load_dwordx2 v[158:159], v165, s[70:71] offset:2560
	global_load_dwordx2 v[160:161], v165, s[70:71] offset:2816
	global_load_dwordx2 v[162:163], v165, s[70:71] offset:3072
	s_waitcnt vmcnt(39)
	s_nop 0
	v_cvt_pk_bf16_f32 v16, v12, v13
	global_store_dword v60, v16, s[68:69]
	v_lshlrev_b32_e32 v14, 16, v73
	v_and_b32_e32 v15, 0xffff0000, v73
	v_pk_fma_f32 v[12:13], v[12:13], v[86:87], v[14:15]
	s_nop 0
	v_cvt_pk_bf16_f32 v16, v12, v13
	global_store_dword v61, v16, s[68:69]
	v_lshlrev_b32_e32 v14, 16, v74
	v_and_b32_e32 v15, 0xffff0000, v74
	v_pk_fma_f32 v[12:13], v[12:13], v[88:89], v[14:15]
	s_nop 0
	v_cvt_pk_bf16_f32 v16, v12, v13
	global_store_dword v62, v16, s[68:69]
	v_lshlrev_b32_e32 v14, 16, v75
	v_and_b32_e32 v15, 0xffff0000, v75
	v_pk_fma_f32 v[12:13], v[12:13], v[90:91], v[14:15]
	s_nop 0
	v_cvt_pk_bf16_f32 v16, v12, v13
	global_store_dword v63, v16, s[68:69]
	v_lshlrev_b32_e32 v14, 16, v76
	v_and_b32_e32 v15, 0xffff0000, v76
	v_pk_fma_f32 v[12:13], v[12:13], v[92:93], v[14:15]
	s_nop 0
	v_cvt_pk_bf16_f32 v16, v12, v13
	global_store_dword v64, v16, s[68:69]
	v_lshlrev_b32_e32 v14, 16, v77
	v_and_b32_e32 v15, 0xffff0000, v77
	v_pk_fma_f32 v[12:13], v[12:13], v[94:95], v[14:15]
	s_nop 0
	v_cvt_pk_bf16_f32 v16, v12, v13
	global_store_dword v65, v16, s[68:69]
	v_lshlrev_b32_e32 v14, 16, v78
	v_and_b32_e32 v15, 0xffff0000, v78
	v_pk_fma_f32 v[12:13], v[12:13], v[96:97], v[14:15]
	s_nop 0
	v_cvt_pk_bf16_f32 v16, v12, v13
	global_store_dword v66, v16, s[68:69]
	v_lshlrev_b32_e32 v14, 16, v79
	v_and_b32_e32 v15, 0xffff0000, v79
	v_pk_fma_f32 v[12:13], v[12:13], v[98:99], v[14:15]
	s_nop 0
	v_cvt_pk_bf16_f32 v16, v12, v13
	global_store_dword v67, v16, s[68:69]
	v_lshlrev_b32_e32 v14, 16, v80
	v_and_b32_e32 v15, 0xffff0000, v80
	v_pk_fma_f32 v[12:13], v[12:13], v[100:101], v[14:15]
	s_nop 0
	v_cvt_pk_bf16_f32 v16, v12, v13
	global_store_dword v68, v16, s[68:69]
	v_lshlrev_b32_e32 v14, 16, v81
	v_and_b32_e32 v15, 0xffff0000, v81
	v_pk_fma_f32 v[12:13], v[12:13], v[102:103], v[14:15]
	s_nop 0
	v_cvt_pk_bf16_f32 v16, v12, v13
	global_store_dword v69, v16, s[68:69]
	v_lshlrev_b32_e32 v14, 16, v82
	v_and_b32_e32 v15, 0xffff0000, v82
	v_pk_fma_f32 v[12:13], v[12:13], v[104:105], v[14:15]
	s_nop 0
	v_cvt_pk_bf16_f32 v16, v12, v13
	global_store_dword v70, v16, s[68:69]
	v_lshlrev_b32_e32 v14, 16, v83
	v_and_b32_e32 v15, 0xffff0000, v83
	v_pk_fma_f32 v[12:13], v[12:13], v[106:107], v[14:15]
	s_nop 0
	v_cvt_pk_bf16_f32 v16, v12, v13
	global_store_dword v71, v16, s[68:69]
	v_lshlrev_b32_e32 v14, 16, v84
	v_and_b32_e32 v15, 0xffff0000, v84
	v_pk_fma_f32 v[12:13], v[12:13], v[108:109], v[14:15]
	s_nop 0
	v_cvt_pk_bf16_f32 v16, v12, v13
	global_store_dword v72, v16, s[68:69]
	v_lshlrev_b32_e32 v14, 16, v85
	v_and_b32_e32 v15, 0xffff0000, v85
	v_pk_fma_f32 v[12:13], v[12:13], v[110:111], v[14:15]
	v_add_u32_e32 v60, 0x1a0000, v2
	global_load_dword v73, v60, s[68:69]
	v_add_u32_e32 v61, 0x1a4000, v2
	global_load_dword v74, v61, s[68:69]
	v_add_u32_e32 v62, 0x1a8000, v2
	global_load_dword v75, v62, s[68:69]
	v_add_u32_e32 v63, 0x1ac000, v2
	global_load_dword v76, v63, s[68:69]
	v_add_u32_e32 v64, 0x1b0000, v2
	global_load_dword v77, v64, s[68:69]
	v_add_u32_e32 v65, 0x1b4000, v2
	global_load_dword v78, v65, s[68:69]
	v_add_u32_e32 v66, 0x1b8000, v2
	global_load_dword v79, v66, s[68:69]
	v_add_u32_e32 v67, 0x1bc000, v2
	global_load_dword v80, v67, s[68:69]
	v_add_u32_e32 v68, 0x1c0000, v2
	global_load_dword v81, v68, s[68:69]
	v_add_u32_e32 v69, 0x1c4000, v2
	global_load_dword v82, v69, s[68:69]
	v_add_u32_e32 v70, 0x1c8000, v2
	global_load_dword v83, v70, s[68:69]
	v_add_u32_e32 v71, 0x1cc000, v2
	global_load_dword v84, v71, s[68:69]
	v_add_u32_e32 v72, 0x1d0000, v2
	global_load_dword v85, v72, s[68:69]
	v_add_u32_e32 v164, 0x6800, v4
	global_load_dwordx2 v[86:87], v164, s[70:71] offset:0
	global_load_dwordx2 v[88:89], v164, s[70:71] offset:256
	global_load_dwordx2 v[90:91], v164, s[70:71] offset:512
	global_load_dwordx2 v[92:93], v164, s[70:71] offset:768
	global_load_dwordx2 v[94:95], v164, s[70:71] offset:1024
	global_load_dwordx2 v[96:97], v164, s[70:71] offset:1280
	global_load_dwordx2 v[98:99], v164, s[70:71] offset:1536
	global_load_dwordx2 v[100:101], v164, s[70:71] offset:1792
	global_load_dwordx2 v[102:103], v164, s[70:71] offset:2048
	global_load_dwordx2 v[104:105], v164, s[70:71] offset:2304
	global_load_dwordx2 v[106:107], v164, s[70:71] offset:2560
	global_load_dwordx2 v[108:109], v164, s[70:71] offset:2816
	global_load_dwordx2 v[110:111], v164, s[70:71] offset:3072
	s_waitcnt vmcnt(39)
	s_nop 0
	v_cvt_pk_bf16_f32 v16, v12, v13
	global_store_dword v112, v16, s[68:69]
	v_lshlrev_b32_e32 v14, 16, v125
	v_and_b32_e32 v15, 0xffff0000, v125
	v_pk_fma_f32 v[12:13], v[12:13], v[138:139], v[14:15]
	s_nop 0
	v_cvt_pk_bf16_f32 v16, v12, v13
	global_store_dword v113, v16, s[68:69]
	v_lshlrev_b32_e32 v14, 16, v126
	v_and_b32_e32 v15, 0xffff0000, v126
	v_pk_fma_f32 v[12:13], v[12:13], v[140:141], v[14:15]
	s_nop 0
	v_cvt_pk_bf16_f32 v16, v12, v13
	global_store_dword v114, v16, s[68:69]
	v_lshlrev_b32_e32 v14, 16, v127
	v_and_b32_e32 v15, 0xffff0000, v127
	v_pk_fma_f32 v[12:13], v[12:13], v[142:143], v[14:15]
	s_nop 0
	v_cvt_pk_bf16_f32 v16, v12, v13
	global_store_dword v115, v16, s[68:69]
	v_lshlrev_b32_e32 v14, 16, v128
	v_and_b32_e32 v15, 0xffff0000, v128
	v_pk_fma_f32 v[12:13], v[12:13], v[144:145], v[14:15]
	s_nop 0
	v_cvt_pk_bf16_f32 v16, v12, v13
	global_store_dword v116, v16, s[68:69]
	v_lshlrev_b32_e32 v14, 16, v129
	v_and_b32_e32 v15, 0xffff0000, v129
	v_pk_fma_f32 v[12:13], v[12:13], v[146:147], v[14:15]
	s_nop 0
	v_cvt_pk_bf16_f32 v16, v12, v13
	global_store_dword v117, v16, s[68:69]
	v_lshlrev_b32_e32 v14, 16, v130
	v_and_b32_e32 v15, 0xffff0000, v130
	v_pk_fma_f32 v[12:13], v[12:13], v[148:149], v[14:15]
	s_nop 0
	v_cvt_pk_bf16_f32 v16, v12, v13
	global_store_dword v118, v16, s[68:69]
	v_lshlrev_b32_e32 v14, 16, v131
	v_and_b32_e32 v15, 0xffff0000, v131
	v_pk_fma_f32 v[12:13], v[12:13], v[150:151], v[14:15]
	s_nop 0
	v_cvt_pk_bf16_f32 v16, v12, v13
	global_store_dword v119, v16, s[68:69]
	v_lshlrev_b32_e32 v14, 16, v132
	v_and_b32_e32 v15, 0xffff0000, v132
	v_pk_fma_f32 v[12:13], v[12:13], v[152:153], v[14:15]
	s_nop 0
	v_cvt_pk_bf16_f32 v16, v12, v13
	global_store_dword v120, v16, s[68:69]
	v_lshlrev_b32_e32 v14, 16, v133
	v_and_b32_e32 v15, 0xffff0000, v133
	v_pk_fma_f32 v[12:13], v[12:13], v[154:155], v[14:15]
	s_nop 0
	v_cvt_pk_bf16_f32 v16, v12, v13
	global_store_dword v121, v16, s[68:69]
	v_lshlrev_b32_e32 v14, 16, v134
	v_and_b32_e32 v15, 0xffff0000, v134
	v_pk_fma_f32 v[12:13], v[12:13], v[156:157], v[14:15]
	s_nop 0
	v_cvt_pk_bf16_f32 v16, v12, v13
	global_store_dword v122, v16, s[68:69]
	v_lshlrev_b32_e32 v14, 16, v135
	v_and_b32_e32 v15, 0xffff0000, v135
	v_pk_fma_f32 v[12:13], v[12:13], v[158:159], v[14:15]
	s_nop 0
	v_cvt_pk_bf16_f32 v16, v12, v13
	global_store_dword v123, v16, s[68:69]
	v_lshlrev_b32_e32 v14, 16, v136
	v_and_b32_e32 v15, 0xffff0000, v136
	v_pk_fma_f32 v[12:13], v[12:13], v[160:161], v[14:15]
	s_nop 0
	v_cvt_pk_bf16_f32 v16, v12, v13
	global_store_dword v124, v16, s[68:69]
	v_lshlrev_b32_e32 v14, 16, v137
	v_and_b32_e32 v15, 0xffff0000, v137
	v_pk_fma_f32 v[12:13], v[12:13], v[162:163], v[14:15]
	v_add_u32_e32 v112, 0x1d4000, v2
	global_load_dword v125, v112, s[68:69]
	v_add_u32_e32 v113, 0x1d8000, v2
	global_load_dword v126, v113, s[68:69]
	v_add_u32_e32 v114, 0x1dc000, v2
	global_load_dword v127, v114, s[68:69]
	v_add_u32_e32 v115, 0x1e0000, v2
	global_load_dword v128, v115, s[68:69]
	v_add_u32_e32 v116, 0x1e4000, v2
	global_load_dword v129, v116, s[68:69]
	v_add_u32_e32 v117, 0x1e8000, v2
	global_load_dword v130, v117, s[68:69]
	v_add_u32_e32 v118, 0x1ec000, v2
	global_load_dword v131, v118, s[68:69]
	v_add_u32_e32 v119, 0x1f0000, v2
	global_load_dword v132, v119, s[68:69]
	v_add_u32_e32 v120, 0x1f4000, v2
	global_load_dword v133, v120, s[68:69]
	v_add_u32_e32 v121, 0x1f8000, v2
	global_load_dword v134, v121, s[68:69]
	v_add_u32_e32 v122, 0x1fc000, v2
	global_load_dword v135, v122, s[68:69]
	v_add_u32_e32 v123, 0x200000, v2
	global_load_dword v136, v123, s[68:69]
	v_add_u32_e32 v124, 0x204000, v2
	global_load_dword v137, v124, s[68:69]
	v_add_u32_e32 v165, 0x7500, v4
	global_load_dwordx2 v[138:139], v165, s[70:71] offset:0
	global_load_dwordx2 v[140:141], v165, s[70:71] offset:256
	global_load_dwordx2 v[142:143], v165, s[70:71] offset:512
	global_load_dwordx2 v[144:145], v165, s[70:71] offset:768
	global_load_dwordx2 v[146:147], v165, s[70:71] offset:1024
	global_load_dwordx2 v[148:149], v165, s[70:71] offset:1280
	global_load_dwordx2 v[150:151], v165, s[70:71] offset:1536
	global_load_dwordx2 v[152:153], v165, s[70:71] offset:1792
	global_load_dwordx2 v[154:155], v165, s[70:71] offset:2048
	global_load_dwordx2 v[156:157], v165, s[70:71] offset:2304
	global_load_dwordx2 v[158:159], v165, s[70:71] offset:2560
	global_load_dwordx2 v[160:161], v165, s[70:71] offset:2816
	global_load_dwordx2 v[162:163], v165, s[70:71] offset:3072
	s_waitcnt vmcnt(39)
	s_nop 0
	v_cvt_pk_bf16_f32 v16, v12, v13
	global_store_dword v60, v16, s[68:69]
	v_lshlrev_b32_e32 v14, 16, v73
	v_and_b32_e32 v15, 0xffff0000, v73
	v_pk_fma_f32 v[12:13], v[12:13], v[86:87], v[14:15]
	s_nop 0
	v_cvt_pk_bf16_f32 v16, v12, v13
	global_store_dword v61, v16, s[68:69]
	v_lshlrev_b32_e32 v14, 16, v74
	v_and_b32_e32 v15, 0xffff0000, v74
	v_pk_fma_f32 v[12:13], v[12:13], v[88:89], v[14:15]
	s_nop 0
	v_cvt_pk_bf16_f32 v16, v12, v13
	global_store_dword v62, v16, s[68:69]
	v_lshlrev_b32_e32 v14, 16, v75
	v_and_b32_e32 v15, 0xffff0000, v75
	v_pk_fma_f32 v[12:13], v[12:13], v[90:91], v[14:15]
	s_nop 0
	v_cvt_pk_bf16_f32 v16, v12, v13
	global_store_dword v63, v16, s[68:69]
	v_lshlrev_b32_e32 v14, 16, v76
	v_and_b32_e32 v15, 0xffff0000, v76
	v_pk_fma_f32 v[12:13], v[12:13], v[92:93], v[14:15]
	s_nop 0
	v_cvt_pk_bf16_f32 v16, v12, v13
	global_store_dword v64, v16, s[68:69]
	v_lshlrev_b32_e32 v14, 16, v77
	v_and_b32_e32 v15, 0xffff0000, v77
	v_pk_fma_f32 v[12:13], v[12:13], v[94:95], v[14:15]
	s_nop 0
	v_cvt_pk_bf16_f32 v16, v12, v13
	global_store_dword v65, v16, s[68:69]
	v_lshlrev_b32_e32 v14, 16, v78
	v_and_b32_e32 v15, 0xffff0000, v78
	v_pk_fma_f32 v[12:13], v[12:13], v[96:97], v[14:15]
	s_nop 0
	v_cvt_pk_bf16_f32 v16, v12, v13
	global_store_dword v66, v16, s[68:69]
	v_lshlrev_b32_e32 v14, 16, v79
	v_and_b32_e32 v15, 0xffff0000, v79
	v_pk_fma_f32 v[12:13], v[12:13], v[98:99], v[14:15]
	s_nop 0
	v_cvt_pk_bf16_f32 v16, v12, v13
	global_store_dword v67, v16, s[68:69]
	v_lshlrev_b32_e32 v14, 16, v80
	v_and_b32_e32 v15, 0xffff0000, v80
	v_pk_fma_f32 v[12:13], v[12:13], v[100:101], v[14:15]
	s_nop 0
	v_cvt_pk_bf16_f32 v16, v12, v13
	global_store_dword v68, v16, s[68:69]
	v_lshlrev_b32_e32 v14, 16, v81
	v_and_b32_e32 v15, 0xffff0000, v81
	v_pk_fma_f32 v[12:13], v[12:13], v[102:103], v[14:15]
	s_nop 0
	v_cvt_pk_bf16_f32 v16, v12, v13
	global_store_dword v69, v16, s[68:69]
	v_lshlrev_b32_e32 v14, 16, v82
	v_and_b32_e32 v15, 0xffff0000, v82
	v_pk_fma_f32 v[12:13], v[12:13], v[104:105], v[14:15]
	s_nop 0
	v_cvt_pk_bf16_f32 v16, v12, v13
	global_store_dword v70, v16, s[68:69]
	v_lshlrev_b32_e32 v14, 16, v83
	v_and_b32_e32 v15, 0xffff0000, v83
	v_pk_fma_f32 v[12:13], v[12:13], v[106:107], v[14:15]
	s_nop 0
	v_cvt_pk_bf16_f32 v16, v12, v13
	global_store_dword v71, v16, s[68:69]
	v_lshlrev_b32_e32 v14, 16, v84
	v_and_b32_e32 v15, 0xffff0000, v84
	v_pk_fma_f32 v[12:13], v[12:13], v[108:109], v[14:15]
	s_nop 0
	v_cvt_pk_bf16_f32 v16, v12, v13
	global_store_dword v72, v16, s[68:69]
	v_lshlrev_b32_e32 v14, 16, v85
	v_and_b32_e32 v15, 0xffff0000, v85
	v_pk_fma_f32 v[12:13], v[12:13], v[110:111], v[14:15]
	s_waitcnt vmcnt(13)
	s_nop 0
	v_cvt_pk_bf16_f32 v16, v12, v13
	global_store_dword v112, v16, s[68:69]
	v_lshlrev_b32_e32 v14, 16, v125
	v_and_b32_e32 v15, 0xffff0000, v125
	v_pk_fma_f32 v[12:13], v[12:13], v[138:139], v[14:15]
	s_nop 0
	v_cvt_pk_bf16_f32 v16, v12, v13
	global_store_dword v113, v16, s[68:69]
	v_lshlrev_b32_e32 v14, 16, v126
	v_and_b32_e32 v15, 0xffff0000, v126
	v_pk_fma_f32 v[12:13], v[12:13], v[140:141], v[14:15]
	s_nop 0
	v_cvt_pk_bf16_f32 v16, v12, v13
	global_store_dword v114, v16, s[68:69]
	v_lshlrev_b32_e32 v14, 16, v127
	v_and_b32_e32 v15, 0xffff0000, v127
	v_pk_fma_f32 v[12:13], v[12:13], v[142:143], v[14:15]
	s_nop 0
	v_cvt_pk_bf16_f32 v16, v12, v13
	global_store_dword v115, v16, s[68:69]
	v_lshlrev_b32_e32 v14, 16, v128
	v_and_b32_e32 v15, 0xffff0000, v128
	v_pk_fma_f32 v[12:13], v[12:13], v[144:145], v[14:15]
	s_nop 0
	v_cvt_pk_bf16_f32 v16, v12, v13
	global_store_dword v116, v16, s[68:69]
	v_lshlrev_b32_e32 v14, 16, v129
	v_and_b32_e32 v15, 0xffff0000, v129
	v_pk_fma_f32 v[12:13], v[12:13], v[146:147], v[14:15]
	s_nop 0
	v_cvt_pk_bf16_f32 v16, v12, v13
	global_store_dword v117, v16, s[68:69]
	v_lshlrev_b32_e32 v14, 16, v130
	v_and_b32_e32 v15, 0xffff0000, v130
	v_pk_fma_f32 v[12:13], v[12:13], v[148:149], v[14:15]
	s_nop 0
	v_cvt_pk_bf16_f32 v16, v12, v13
	global_store_dword v118, v16, s[68:69]
	v_lshlrev_b32_e32 v14, 16, v131
	v_and_b32_e32 v15, 0xffff0000, v131
	v_pk_fma_f32 v[12:13], v[12:13], v[150:151], v[14:15]
	s_nop 0
	v_cvt_pk_bf16_f32 v16, v12, v13
	global_store_dword v119, v16, s[68:69]
	v_lshlrev_b32_e32 v14, 16, v132
	v_and_b32_e32 v15, 0xffff0000, v132
	v_pk_fma_f32 v[12:13], v[12:13], v[152:153], v[14:15]
	s_nop 0
	v_cvt_pk_bf16_f32 v16, v12, v13
	global_store_dword v120, v16, s[68:69]
	v_lshlrev_b32_e32 v14, 16, v133
	v_and_b32_e32 v15, 0xffff0000, v133
	v_pk_fma_f32 v[12:13], v[12:13], v[154:155], v[14:15]
	s_nop 0
	v_cvt_pk_bf16_f32 v16, v12, v13
	global_store_dword v121, v16, s[68:69]
	v_lshlrev_b32_e32 v14, 16, v134
	v_and_b32_e32 v15, 0xffff0000, v134
	v_pk_fma_f32 v[12:13], v[12:13], v[156:157], v[14:15]
	s_nop 0
	v_cvt_pk_bf16_f32 v16, v12, v13
	global_store_dword v122, v16, s[68:69]
	v_lshlrev_b32_e32 v14, 16, v135
	v_and_b32_e32 v15, 0xffff0000, v135
	v_pk_fma_f32 v[12:13], v[12:13], v[158:159], v[14:15]
	s_nop 0
	v_cvt_pk_bf16_f32 v16, v12, v13
	global_store_dword v123, v16, s[68:69]
	v_lshlrev_b32_e32 v14, 16, v136
	v_and_b32_e32 v15, 0xffff0000, v136
	v_pk_fma_f32 v[12:13], v[12:13], v[160:161], v[14:15]
	s_nop 0
	v_cvt_pk_bf16_f32 v16, v12, v13
	global_store_dword v124, v16, s[68:69]
	v_lshlrev_b32_e32 v14, 16, v137
	v_and_b32_e32 v15, 0xffff0000, v137
	v_pk_fma_f32 v[12:13], v[12:13], v[162:163], v[14:15]
	v_add_u32_e32 v30, s6, v30
	s_mov_b32 s9, 0xffff
	v_cmp_lt_i32_e32 vcc, s9, v30
	s_or_b64 s[2:3], vcc, s[2:3]
	v_add_u32_e32 v29, s8, v29
	s_andn2_b64 exec, exec, s[2:3]
	s_cbranch_execnz .LBB0_221
